# GEMM1 epilogue gate sections: per-column lower-bound quads loaded once per column block and reused across the 8 row blocks (28 of 32 loads and their vmcnt(0) drains removed per tile)
# speedup vs baseline: 1.0126x; 1.0047x over previous
.LBB0_143:
	s_add_i32 s6, s6, s50
	v_add_u32_e32 v131, s6, v213
	v_ashrrev_i32_e32 v133, 11, v131
	v_cmp_lt_u32_e32 vcc, s24, v131
	v_cmp_ne_u32_e64 s[0:1], 4, v133
	s_mov_b32 s52, s7
	v_and_b32_e32 v130, 0x7ff, v131
	s_and_b64 s[44:45], vcc, s[0:1]
	s_and_saveexec_b64 s[0:1], s[44:45]
	s_xor_b64 s[0:1], exec, s[0:1]
	s_cbranch_execz .LBB0_147
	v_cmp_ne_u32_e32 vcc, 3, v133
	s_and_saveexec_b64 s[2:3], vcc
	s_cbranch_execz .LBB0_146
	v_and_b32_e32 v128, 0xfffff800, v131
	v_add_u32_e32 v128, 0xfffff800, v128
	v_ashrrev_i32_e32 v129, 31, v128
	v_lshl_add_u64 v[128:129], v[128:129], 2, s[90:91]
	v_lshlrev_b32_e32 v176, 2, v130
	v_lshl_add_u64 v[128:129], v[128:129], 0, v[176:177]
	global_load_dwordx4 v[134:137], v[128:129], off
	v_mul_f32_e32 v124, 0xbfb8aa3b, v124
	v_exp_f32_e32 v124, v124
	v_mul_f32_e32 v125, 0xbfb8aa3b, v125
	v_exp_f32_e32 v125, v125
	v_mul_f32_e32 v126, 0xbfb8aa3b, v126
	v_exp_f32_e32 v126, v126
	v_mul_f32_e32 v127, 0xbfb8aa3b, v127
	v_exp_f32_e32 v127, v127
	v_add_f32_e32 v124, 1.0, v124
	v_rcp_f32_e32 v124, v124
	v_add_f32_e32 v125, 1.0, v125
	v_rcp_f32_e32 v125, v125
	v_add_f32_e32 v126, 1.0, v126
	v_rcp_f32_e32 v126, v126
	v_add_f32_e32 v127, 1.0, v127
	v_rcp_f32_e32 v127, v127
	s_waitcnt vmcnt(0)
	v_mov_b64_e32 v[144:145], v[134:135]
	v_mov_b64_e32 v[146:147], v[136:137]
	v_sub_f32_e32 v128, 1.0, v134
	v_fma_f32 v124, v124, v128, v134
	v_sub_f32_e32 v128, 1.0, v135
	v_fma_f32 v125, v125, v128, v135
	v_sub_f32_e32 v128, 1.0, v136
	v_fma_f32 v126, v126, v128, v136
	v_sub_f32_e32 v128, 1.0, v137
	v_fmac_f32_e32 v137, v127, v128
	v_log_f32_e32 v124, v124
	v_log_f32_e32 v125, v125
	v_log_f32_e32 v126, v126
	v_log_f32_e32 v127, v137
	v_pk_mul_f32 v[124:125], v[124:125], s[96:97] op_sel_hi:[1,0]
	v_pk_mul_f32 v[126:127], v[126:127], s[96:97] op_sel_hi:[1,0]

.LBB0_149:
	s_or_b64 exec, exec, s[0:1]
	v_add_u32_e32 v134, 16, v131
	v_ashrrev_i32_e32 v135, 11, v134
	v_cmp_lt_u32_e32 vcc, s24, v134
	v_cmp_ne_u32_e64 s[0:1], 4, v135
	v_and_b32_e32 v132, 0x7ff, v134
	s_and_b64 s[46:47], vcc, s[0:1]
	s_and_saveexec_b64 s[0:1], s[46:47]
	s_xor_b64 s[0:1], exec, s[0:1]
	s_cbranch_execz .LBB0_153
	v_cmp_ne_u32_e32 vcc, 3, v135
	s_and_saveexec_b64 s[2:3], vcc
	s_cbranch_execz .LBB0_152
	v_and_b32_e32 v128, 0xfffff800, v134
	v_add_u32_e32 v128, 0xfffff800, v128
	v_ashrrev_i32_e32 v129, 31, v128
	v_lshl_add_u64 v[128:129], v[128:129], 2, s[90:91]
	v_lshlrev_b32_e32 v176, 2, v132
	v_lshl_add_u64 v[128:129], v[128:129], 0, v[176:177]
	global_load_dwordx4 v[136:139], v[128:129], off
	v_mul_f32_e32 v120, 0xbfb8aa3b, v120
	v_exp_f32_e32 v120, v120
	v_mul_f32_e32 v121, 0xbfb8aa3b, v121
	v_exp_f32_e32 v121, v121
	v_mul_f32_e32 v122, 0xbfb8aa3b, v122
	v_exp_f32_e32 v122, v122
	v_mul_f32_e32 v123, 0xbfb8aa3b, v123
	v_exp_f32_e32 v123, v123
	v_add_f32_e32 v120, 1.0, v120
	v_rcp_f32_e32 v120, v120
	v_add_f32_e32 v121, 1.0, v121
	v_rcp_f32_e32 v121, v121
	v_add_f32_e32 v122, 1.0, v122
	v_rcp_f32_e32 v122, v122
	v_add_f32_e32 v123, 1.0, v123
	v_rcp_f32_e32 v123, v123
	s_waitcnt vmcnt(0)
	v_mov_b64_e32 v[148:149], v[136:137]
	v_mov_b64_e32 v[150:151], v[138:139]
	v_sub_f32_e32 v128, 1.0, v136
	v_fma_f32 v120, v120, v128, v136
	v_sub_f32_e32 v128, 1.0, v137
	v_fma_f32 v121, v121, v128, v137
	v_sub_f32_e32 v128, 1.0, v138
	v_fma_f32 v122, v122, v128, v138
	v_sub_f32_e32 v128, 1.0, v139
	v_fmac_f32_e32 v139, v123, v128
	v_log_f32_e32 v120, v120
	v_log_f32_e32 v121, v121
	v_log_f32_e32 v122, v122
	v_log_f32_e32 v123, v139
	v_pk_mul_f32 v[120:121], v[120:121], s[96:97] op_sel_hi:[1,0]
	v_pk_mul_f32 v[122:123], v[122:123], s[96:97] op_sel_hi:[1,0]

.LBB0_155:
	s_or_b64 exec, exec, s[0:1]
	v_cvt_pk_bf16_f32 v138, v120, v121
	v_add_u32_e32 v120, s6, v215
	v_add_u32_e32 v128, s48, v214
	v_cvt_pk_bf16_f32 v139, v122, v123
	v_ashrrev_i32_e32 v122, 11, v120
	v_ashrrev_i32_e32 v129, 31, v128
	v_cvt_pk_bf16_f32 v136, v124, v125
	v_and_b32_e32 v124, 0x7ff, v120
	v_mul_hi_i32_i24_e32 v121, 0x4400, v122
	v_mul_i32_i24_e32 v120, 0x4400, v122
	v_lshl_add_u64 v[122:123], v[120:121], 0, v[128:129]
	v_lshlrev_b64 v[122:123], 12, v[122:123]
	v_cvt_pk_bf16_f32 v137, v126, v127
	v_lshl_add_u64 v[122:123], s[86:87], 0, v[122:123]
	v_lshlrev_b32_e32 v176, 1, v124
	v_permlane16_swap_b32_e32 v136, v138
	v_permlane16_swap_b32_e32 v137, v139
	v_lshl_add_u64 v[122:123], v[122:123], 0, v[176:177]
	s_add_i32 s6, s6, 32
	global_store_dwordx4 v[122:123], v[136:139], off
	v_add_u32_e32 v123, s6, v213
	v_ashrrev_i32_e32 v126, 11, v123
	v_cmp_lt_u32_e32 vcc, s24, v123
	v_cmp_ne_u32_e64 s[0:1], 4, v126
	v_and_b32_e32 v122, 0x7ff, v123
	s_and_b64 s[48:49], vcc, s[0:1]
	s_and_saveexec_b64 s[0:1], s[48:49]
	s_xor_b64 s[0:1], exec, s[0:1]
	s_cbranch_execz .LBB0_159
	v_cmp_ne_u32_e32 vcc, 3, v126
	s_and_saveexec_b64 s[2:3], vcc
	s_cbranch_execz .LBB0_158
	v_and_b32_e32 v124, 0xfffff800, v123
	v_add_u32_e32 v124, 0xfffff800, v124
	v_ashrrev_i32_e32 v125, 31, v124
	v_lshl_add_u64 v[124:125], v[124:125], 2, s[90:91]
	v_lshlrev_b32_e32 v136, 2, v122
	v_mov_b32_e32 v137, v177
	v_lshl_add_u64 v[124:125], v[124:125], 0, v[136:137]
	global_load_dwordx4 v[136:139], v[124:125], off
	v_mul_f32_e32 v116, 0xbfb8aa3b, v116
	v_exp_f32_e32 v116, v116
	v_mul_f32_e32 v117, 0xbfb8aa3b, v117
	v_exp_f32_e32 v117, v117
	v_mul_f32_e32 v118, 0xbfb8aa3b, v118
	v_exp_f32_e32 v118, v118
	v_mul_f32_e32 v119, 0xbfb8aa3b, v119
	v_exp_f32_e32 v119, v119
	v_add_f32_e32 v116, 1.0, v116
	v_rcp_f32_e32 v116, v116
	v_add_f32_e32 v117, 1.0, v117
	v_rcp_f32_e32 v117, v117
	v_add_f32_e32 v118, 1.0, v118
	v_rcp_f32_e32 v118, v118
	v_add_f32_e32 v119, 1.0, v119
	v_rcp_f32_e32 v119, v119
	s_waitcnt vmcnt(0)
	v_mov_b64_e32 v[152:153], v[136:137]
	v_mov_b64_e32 v[154:155], v[138:139]
	v_sub_f32_e32 v124, 1.0, v136
	v_fma_f32 v116, v116, v124, v136
	v_sub_f32_e32 v124, 1.0, v137
	v_fma_f32 v117, v117, v124, v137
	v_sub_f32_e32 v124, 1.0, v138
	v_fma_f32 v118, v118, v124, v138
	v_sub_f32_e32 v124, 1.0, v139
	v_fmac_f32_e32 v139, v119, v124
	v_log_f32_e32 v116, v116
	v_log_f32_e32 v117, v117
	v_log_f32_e32 v118, v118
	v_log_f32_e32 v119, v139
	v_pk_mul_f32 v[116:117], v[116:117], s[96:97] op_sel_hi:[1,0]
	v_pk_mul_f32 v[118:119], v[118:119], s[96:97] op_sel_hi:[1,0]

.LBB0_161:
	s_or_b64 exec, exec, s[0:1]
	v_add_u32_e32 v125, 16, v123
	v_ashrrev_i32_e32 v127, 11, v125
	v_cmp_lt_u32_e32 vcc, s24, v125
	v_cmp_ne_u32_e64 s[0:1], 4, v127
	v_and_b32_e32 v124, 0x7ff, v125
	s_and_b64 s[0:1], vcc, s[0:1]
	s_and_saveexec_b64 s[2:3], s[0:1]
	s_xor_b64 s[2:3], exec, s[2:3]
	s_cbranch_execz .LBB0_165
	v_cmp_ne_u32_e32 vcc, 3, v127
	s_and_saveexec_b64 s[8:9], vcc
	s_cbranch_execz .LBB0_164
	v_and_b32_e32 v136, 0xfffff800, v125
	v_add_u32_e32 v136, 0xfffff800, v136
	v_ashrrev_i32_e32 v137, 31, v136
	v_lshl_add_u64 v[136:137], v[136:137], 2, s[90:91]
	v_lshlrev_b32_e32 v138, 2, v124
	v_mov_b32_e32 v139, v177
	v_lshl_add_u64 v[136:137], v[136:137], 0, v[138:139]
	global_load_dwordx4 v[136:139], v[136:137], off
	v_mul_f32_e32 v112, 0xbfb8aa3b, v112
	v_exp_f32_e32 v112, v112
	v_mul_f32_e32 v113, 0xbfb8aa3b, v113
	v_exp_f32_e32 v113, v113
	v_mul_f32_e32 v114, 0xbfb8aa3b, v114
	v_exp_f32_e32 v114, v114
	v_mul_f32_e32 v115, 0xbfb8aa3b, v115
	v_exp_f32_e32 v115, v115
	v_add_f32_e32 v112, 1.0, v112
	v_rcp_f32_e32 v112, v112
	v_add_f32_e32 v113, 1.0, v113
	v_rcp_f32_e32 v113, v113
	v_add_f32_e32 v114, 1.0, v114
	v_rcp_f32_e32 v114, v114
	v_add_f32_e32 v115, 1.0, v115
	v_rcp_f32_e32 v115, v115
	s_waitcnt vmcnt(0)
	v_mov_b64_e32 v[156:157], v[136:137]
	v_mov_b64_e32 v[158:159], v[138:139]
	v_sub_f32_e32 v140, 1.0, v136
	v_fma_f32 v112, v112, v140, v136
	v_sub_f32_e32 v136, 1.0, v137
	v_fma_f32 v113, v113, v136, v137
	v_sub_f32_e32 v136, 1.0, v138
	v_fma_f32 v114, v114, v136, v138
	v_sub_f32_e32 v136, 1.0, v139
	v_fmac_f32_e32 v139, v115, v136
	v_log_f32_e32 v112, v112
	v_log_f32_e32 v113, v113
	v_log_f32_e32 v114, v114
	v_log_f32_e32 v115, v139
	v_pk_mul_f32 v[112:113], v[112:113], s[96:97] op_sel_hi:[1,0]
	v_pk_mul_f32 v[114:115], v[114:115], s[96:97] op_sel_hi:[1,0]

.LBB0_167:
	s_or_b64 exec, exec, s[2:3]
	v_cvt_pk_bf16_f32 v138, v112, v113
	v_add_u32_e32 v112, s6, v215
	v_cvt_pk_bf16_f32 v139, v114, v115
	v_ashrrev_i32_e32 v114, 11, v112
	v_cvt_pk_bf16_f32 v137, v118, v119
	v_and_b32_e32 v118, 0x7ff, v112
	v_mul_hi_i32_i24_e32 v113, 0x4400, v114
	v_mul_i32_i24_e32 v112, 0x4400, v114
	v_lshl_add_u64 v[114:115], v[112:113], 0, v[128:129]
	v_lshlrev_b64 v[114:115], 12, v[114:115]
	v_cvt_pk_bf16_f32 v136, v116, v117
	v_lshl_add_u64 v[116:117], s[86:87], 0, v[114:115]
	v_lshlrev_b32_e32 v114, 1, v118
	v_mov_b32_e32 v115, v177
	v_permlane16_swap_b32_e32 v136, v138
	v_permlane16_swap_b32_e32 v137, v139
	v_lshl_add_u64 v[116:117], v[116:117], 0, v[114:115]
	global_store_dwordx4 v[116:117], v[136:139], off
	s_and_saveexec_b64 s[2:3], s[44:45]
	s_xor_b64 s[2:3], exec, s[2:3]
	s_cbranch_execz .LBB0_175
	v_cmp_ne_u32_e32 vcc, 3, v133
	s_and_saveexec_b64 s[8:9], vcc
	s_cbranch_execz .LBB0_170
	v_and_b32_e32 v115, 0xfffff800, v131
	v_add_u32_e32 v116, 0xfffff800, v115
	v_ashrrev_i32_e32 v117, 31, v116
	v_lshl_add_u64 v[116:117], v[116:117], 2, s[90:91]
	v_lshlrev_b32_e32 v118, 2, v130
	v_mov_b32_e32 v119, v177
	v_lshl_add_u64 v[116:117], v[116:117], 0, v[118:119]
	v_mov_b64_e32 v[116:117], v[144:145]
	v_mov_b64_e32 v[118:119], v[146:147]
	v_mul_f32_e32 v108, 0xbfb8aa3b, v108
	v_exp_f32_e32 v108, v108
	v_mul_f32_e32 v109, 0xbfb8aa3b, v109
	v_exp_f32_e32 v109, v109
	v_mul_f32_e32 v110, 0xbfb8aa3b, v110
	v_exp_f32_e32 v110, v110
	v_mul_f32_e32 v111, 0xbfb8aa3b, v111
	v_exp_f32_e32 v111, v111
	v_add_f32_e32 v108, 1.0, v108
	v_rcp_f32_e32 v108, v108
	v_add_f32_e32 v109, 1.0, v109
	v_rcp_f32_e32 v109, v109
	v_add_f32_e32 v110, 1.0, v110
	v_rcp_f32_e32 v110, v110
	v_add_f32_e32 v111, 1.0, v111
	v_rcp_f32_e32 v111, v111
	v_sub_f32_e32 v115, 1.0, v116
	v_fma_f32 v108, v108, v115, v116
	v_sub_f32_e32 v115, 1.0, v117
	v_fma_f32 v109, v109, v115, v117
	v_sub_f32_e32 v115, 1.0, v118
	v_fma_f32 v110, v110, v115, v118
	v_sub_f32_e32 v115, 1.0, v119
	v_fmac_f32_e32 v119, v111, v115
	v_log_f32_e32 v108, v108
	v_log_f32_e32 v109, v109
	v_log_f32_e32 v110, v110
	v_log_f32_e32 v111, v119
	v_pk_mul_f32 v[108:109], v[108:109], s[96:97] op_sel_hi:[1,0]
	v_pk_mul_f32 v[110:111], v[110:111], s[96:97] op_sel_hi:[1,0]

.LBB0_172:
	v_cmp_ne_u32_e32 vcc, 3, v135
	s_and_saveexec_b64 s[8:9], vcc
	s_cbranch_execz .LBB0_174
	v_and_b32_e32 v115, 0xfffff800, v134
	v_add_u32_e32 v116, 0xfffff800, v115
	v_ashrrev_i32_e32 v117, 31, v116
	v_lshl_add_u64 v[116:117], v[116:117], 2, s[90:91]
	v_lshlrev_b32_e32 v118, 2, v132
	v_mov_b32_e32 v119, v177
	v_lshl_add_u64 v[116:117], v[116:117], 0, v[118:119]
	v_mov_b64_e32 v[116:117], v[148:149]
	v_mov_b64_e32 v[118:119], v[150:151]
	v_mul_f32_e32 v104, 0xbfb8aa3b, v104
	v_exp_f32_e32 v104, v104
	v_mul_f32_e32 v105, 0xbfb8aa3b, v105
	v_exp_f32_e32 v105, v105
	v_mul_f32_e32 v106, 0xbfb8aa3b, v106
	v_exp_f32_e32 v106, v106
	v_mul_f32_e32 v107, 0xbfb8aa3b, v107
	v_exp_f32_e32 v107, v107
	v_add_f32_e32 v104, 1.0, v104
	v_rcp_f32_e32 v104, v104
	v_add_f32_e32 v105, 1.0, v105
	v_rcp_f32_e32 v105, v105
	v_add_f32_e32 v106, 1.0, v106
	v_rcp_f32_e32 v106, v106
	v_add_f32_e32 v107, 1.0, v107
	v_rcp_f32_e32 v107, v107
	v_sub_f32_e32 v115, 1.0, v116
	v_fma_f32 v104, v104, v115, v116
	v_sub_f32_e32 v115, 1.0, v117
	v_fma_f32 v105, v105, v115, v117
	v_sub_f32_e32 v115, 1.0, v118
	v_fma_f32 v106, v106, v115, v118
	v_sub_f32_e32 v115, 1.0, v119
	v_fmac_f32_e32 v119, v107, v115
	v_log_f32_e32 v104, v104
	v_log_f32_e32 v105, v105
	v_log_f32_e32 v106, v106
	v_log_f32_e32 v107, v119
	v_pk_mul_f32 v[104:105], v[104:105], s[96:97] op_sel_hi:[1,0]
	v_pk_mul_f32 v[106:107], v[106:107], s[96:97] op_sel_hi:[1,0]

.LBB0_179:
	s_or_b64 exec, exec, s[2:3]
	v_add_u32_e32 v116, 16, v128
	v_ashrrev_i32_e32 v117, 31, v116
	v_cvt_pk_bf16_f32 v138, v104, v105
	v_lshl_add_u64 v[104:105], v[120:121], 0, v[116:117]
	v_lshlrev_b64 v[104:105], 12, v[104:105]
	v_cvt_pk_bf16_f32 v137, v110, v111
	v_cvt_pk_bf16_f32 v136, v108, v109
	v_cvt_pk_bf16_f32 v139, v106, v107
	v_lshl_add_u64 v[104:105], s[86:87], 0, v[104:105]
	v_permlane16_swap_b32_e32 v136, v138
	v_permlane16_swap_b32_e32 v137, v139
	v_lshl_add_u64 v[104:105], v[104:105], 0, v[176:177]
	global_store_dwordx4 v[104:105], v[136:139], off
	s_and_saveexec_b64 s[2:3], s[48:49]
	s_xor_b64 s[2:3], exec, s[2:3]
	s_cbranch_execz .LBB0_187
	v_cmp_ne_u32_e32 vcc, 3, v126
	s_and_saveexec_b64 s[8:9], vcc
	s_cbranch_execz .LBB0_182
	v_and_b32_e32 v104, 0xfffff800, v123
	v_add_u32_e32 v104, 0xfffff800, v104
	v_ashrrev_i32_e32 v105, 31, v104
	v_lshl_add_u64 v[104:105], v[104:105], 2, s[90:91]
	v_lshlrev_b32_e32 v106, 2, v122
	v_mov_b32_e32 v107, v177
	v_lshl_add_u64 v[104:105], v[104:105], 0, v[106:107]
	v_mov_b64_e32 v[104:105], v[152:153]
	v_mov_b64_e32 v[106:107], v[154:155]
	v_mul_f32_e32 v100, 0xbfb8aa3b, v100
	v_exp_f32_e32 v100, v100
	v_mul_f32_e32 v101, 0xbfb8aa3b, v101
	v_exp_f32_e32 v101, v101
	v_mul_f32_e32 v102, 0xbfb8aa3b, v102
	v_exp_f32_e32 v102, v102
	v_mul_f32_e32 v103, 0xbfb8aa3b, v103
	v_exp_f32_e32 v103, v103
	v_add_f32_e32 v100, 1.0, v100
	v_rcp_f32_e32 v100, v100
	v_add_f32_e32 v101, 1.0, v101
	v_rcp_f32_e32 v101, v101
	v_add_f32_e32 v102, 1.0, v102
	v_rcp_f32_e32 v102, v102
	v_add_f32_e32 v103, 1.0, v103
	v_rcp_f32_e32 v103, v103
	v_sub_f32_e32 v108, 1.0, v104
	v_fma_f32 v100, v100, v108, v104
	v_sub_f32_e32 v104, 1.0, v105
	v_fma_f32 v101, v101, v104, v105
	v_sub_f32_e32 v104, 1.0, v106
	v_fma_f32 v102, v102, v104, v106
	v_sub_f32_e32 v104, 1.0, v107
	v_fmac_f32_e32 v107, v103, v104
	v_log_f32_e32 v100, v100
	v_log_f32_e32 v101, v101
	v_log_f32_e32 v102, v102
	v_log_f32_e32 v103, v107
	v_pk_mul_f32 v[100:101], v[100:101], s[96:97] op_sel_hi:[1,0]
	v_pk_mul_f32 v[102:103], v[102:103], s[96:97] op_sel_hi:[1,0]

.LBB0_184:
	v_cmp_ne_u32_e32 vcc, 3, v127
	s_and_saveexec_b64 s[8:9], vcc
	s_cbranch_execz .LBB0_186
	v_and_b32_e32 v104, 0xfffff800, v125
	v_add_u32_e32 v104, 0xfffff800, v104
	v_ashrrev_i32_e32 v105, 31, v104
	v_lshl_add_u64 v[104:105], v[104:105], 2, s[90:91]
	v_lshlrev_b32_e32 v106, 2, v124
	v_mov_b32_e32 v107, v177
	v_lshl_add_u64 v[104:105], v[104:105], 0, v[106:107]
	v_mov_b64_e32 v[104:105], v[156:157]
	v_mov_b64_e32 v[106:107], v[158:159]
	v_mul_f32_e32 v96, 0xbfb8aa3b, v96
	v_exp_f32_e32 v96, v96
	v_mul_f32_e32 v97, 0xbfb8aa3b, v97
	v_exp_f32_e32 v97, v97
	v_mul_f32_e32 v98, 0xbfb8aa3b, v98
	v_exp_f32_e32 v98, v98
	v_mul_f32_e32 v99, 0xbfb8aa3b, v99
	v_exp_f32_e32 v99, v99
	v_add_f32_e32 v96, 1.0, v96
	v_rcp_f32_e32 v96, v96
	v_add_f32_e32 v97, 1.0, v97
	v_rcp_f32_e32 v97, v97
	v_add_f32_e32 v98, 1.0, v98
	v_rcp_f32_e32 v98, v98
	v_add_f32_e32 v99, 1.0, v99
	v_rcp_f32_e32 v99, v99
	v_sub_f32_e32 v108, 1.0, v104
	v_fma_f32 v96, v96, v108, v104
	v_sub_f32_e32 v104, 1.0, v105
	v_fma_f32 v97, v97, v104, v105
	v_sub_f32_e32 v104, 1.0, v106
	v_fma_f32 v98, v98, v104, v106
	v_sub_f32_e32 v104, 1.0, v107
	v_fmac_f32_e32 v107, v99, v104
	v_log_f32_e32 v96, v96
	v_log_f32_e32 v97, v97
	v_log_f32_e32 v98, v98
	v_log_f32_e32 v99, v107
	v_pk_mul_f32 v[96:97], v[96:97], s[96:97] op_sel_hi:[1,0]
	v_pk_mul_f32 v[98:99], v[98:99], s[96:97] op_sel_hi:[1,0]

.LBB0_191:
	s_or_b64 exec, exec, s[2:3]
	v_cvt_pk_bf16_f32 v104, v96, v97
	v_lshl_add_u64 v[96:97], v[112:113], 0, v[116:117]
	v_lshlrev_b64 v[96:97], 12, v[96:97]
	v_cvt_pk_bf16_f32 v103, v102, v103
	v_cvt_pk_bf16_f32 v102, v100, v101
	v_cvt_pk_bf16_f32 v105, v98, v99
	v_lshl_add_u64 v[96:97], s[86:87], 0, v[96:97]
	v_mov_b32_e32 v115, v177
	v_permlane16_swap_b32_e32 v102, v104
	v_permlane16_swap_b32_e32 v103, v105
	v_lshl_add_u64 v[96:97], v[96:97], 0, v[114:115]
	global_store_dwordx4 v[96:97], v[102:105], off
	s_and_saveexec_b64 s[2:3], s[44:45]
	s_xor_b64 s[2:3], exec, s[2:3]
	s_cbranch_execz .LBB0_199
	v_cmp_ne_u32_e32 vcc, 3, v133
	s_and_saveexec_b64 s[8:9], vcc
	s_cbranch_execz .LBB0_194
	v_and_b32_e32 v96, 0xfffff800, v131
	v_add_u32_e32 v96, 0xfffff800, v96
	v_ashrrev_i32_e32 v97, 31, v96
	v_lshl_add_u64 v[96:97], v[96:97], 2, s[90:91]
	v_lshlrev_b32_e32 v98, 2, v130
	v_mov_b32_e32 v99, v177
	v_lshl_add_u64 v[96:97], v[96:97], 0, v[98:99]
	v_mov_b64_e32 v[96:97], v[144:145]
	v_mov_b64_e32 v[98:99], v[146:147]
	v_mul_f32_e32 v92, 0xbfb8aa3b, v92
	v_exp_f32_e32 v92, v92
	v_mul_f32_e32 v93, 0xbfb8aa3b, v93
	v_exp_f32_e32 v93, v93
	v_mul_f32_e32 v94, 0xbfb8aa3b, v94
	v_exp_f32_e32 v94, v94
	v_mul_f32_e32 v95, 0xbfb8aa3b, v95
	v_exp_f32_e32 v95, v95
	v_add_f32_e32 v92, 1.0, v92
	v_rcp_f32_e32 v92, v92
	v_add_f32_e32 v93, 1.0, v93
	v_rcp_f32_e32 v93, v93
	v_add_f32_e32 v94, 1.0, v94
	v_rcp_f32_e32 v94, v94
	v_add_f32_e32 v95, 1.0, v95
	v_rcp_f32_e32 v95, v95
	v_sub_f32_e32 v100, 1.0, v96
	v_fma_f32 v92, v92, v100, v96
	v_sub_f32_e32 v96, 1.0, v97
	v_fma_f32 v93, v93, v96, v97
	v_sub_f32_e32 v96, 1.0, v98
	v_fma_f32 v94, v94, v96, v98
	v_sub_f32_e32 v96, 1.0, v99
	v_fmac_f32_e32 v99, v95, v96
	v_log_f32_e32 v92, v92
	v_log_f32_e32 v93, v93
	v_log_f32_e32 v94, v94
	v_log_f32_e32 v95, v99
	v_pk_mul_f32 v[92:93], v[92:93], s[96:97] op_sel_hi:[1,0]
	v_pk_mul_f32 v[94:95], v[94:95], s[96:97] op_sel_hi:[1,0]

.LBB0_196:
	v_cmp_ne_u32_e32 vcc, 3, v135
	s_and_saveexec_b64 s[8:9], vcc
	s_cbranch_execz .LBB0_198
	v_and_b32_e32 v96, 0xfffff800, v134
	v_add_u32_e32 v96, 0xfffff800, v96
	v_ashrrev_i32_e32 v97, 31, v96
	v_lshl_add_u64 v[96:97], v[96:97], 2, s[90:91]
	v_lshlrev_b32_e32 v98, 2, v132
	v_mov_b32_e32 v99, v177
	v_lshl_add_u64 v[96:97], v[96:97], 0, v[98:99]
	v_mov_b64_e32 v[96:97], v[148:149]
	v_mov_b64_e32 v[98:99], v[150:151]
	v_mul_f32_e32 v88, 0xbfb8aa3b, v88
	v_exp_f32_e32 v88, v88
	v_mul_f32_e32 v89, 0xbfb8aa3b, v89
	v_exp_f32_e32 v89, v89
	v_mul_f32_e32 v90, 0xbfb8aa3b, v90
	v_exp_f32_e32 v90, v90
	v_mul_f32_e32 v91, 0xbfb8aa3b, v91
	v_exp_f32_e32 v91, v91
	v_add_f32_e32 v88, 1.0, v88
	v_rcp_f32_e32 v88, v88
	v_add_f32_e32 v89, 1.0, v89
	v_rcp_f32_e32 v89, v89
	v_add_f32_e32 v90, 1.0, v90
	v_rcp_f32_e32 v90, v90
	v_add_f32_e32 v91, 1.0, v91
	v_rcp_f32_e32 v91, v91
	v_sub_f32_e32 v100, 1.0, v96
	v_fma_f32 v88, v88, v100, v96
	v_sub_f32_e32 v96, 1.0, v97
	v_fma_f32 v89, v89, v96, v97
	v_sub_f32_e32 v96, 1.0, v98
	v_fma_f32 v90, v90, v96, v98
	v_sub_f32_e32 v96, 1.0, v99
	v_fmac_f32_e32 v99, v91, v96
	v_log_f32_e32 v88, v88
	v_log_f32_e32 v89, v89
	v_log_f32_e32 v90, v90
	v_log_f32_e32 v91, v99
	v_pk_mul_f32 v[88:89], v[88:89], s[96:97] op_sel_hi:[1,0]
	v_pk_mul_f32 v[90:91], v[90:91], s[96:97] op_sel_hi:[1,0]

.LBB0_203:
	s_or_b64 exec, exec, s[2:3]
	v_add_u32_e32 v96, 32, v128
	v_ashrrev_i32_e32 v97, 31, v96
	v_cvt_pk_bf16_f32 v100, v88, v89
	v_lshl_add_u64 v[88:89], v[120:121], 0, v[96:97]
	v_lshlrev_b64 v[88:89], 12, v[88:89]
	v_cvt_pk_bf16_f32 v99, v94, v95
	v_cvt_pk_bf16_f32 v98, v92, v93
	v_cvt_pk_bf16_f32 v101, v90, v91
	v_lshl_add_u64 v[88:89], s[86:87], 0, v[88:89]
	v_permlane16_swap_b32_e32 v98, v100
	v_permlane16_swap_b32_e32 v99, v101
	v_lshl_add_u64 v[88:89], v[88:89], 0, v[176:177]
	global_store_dwordx4 v[88:89], v[98:101], off
	s_and_saveexec_b64 s[2:3], s[48:49]
	s_xor_b64 s[2:3], exec, s[2:3]
	s_cbranch_execz .LBB0_211
	v_cmp_ne_u32_e32 vcc, 3, v126
	s_and_saveexec_b64 s[8:9], vcc
	s_cbranch_execz .LBB0_206
	v_and_b32_e32 v88, 0xfffff800, v123
	v_add_u32_e32 v88, 0xfffff800, v88
	v_ashrrev_i32_e32 v89, 31, v88
	v_lshl_add_u64 v[88:89], v[88:89], 2, s[90:91]
	v_lshlrev_b32_e32 v90, 2, v122
	v_mov_b32_e32 v91, v177
	v_lshl_add_u64 v[88:89], v[88:89], 0, v[90:91]
	v_mov_b64_e32 v[88:89], v[152:153]
	v_mov_b64_e32 v[90:91], v[154:155]
	v_mul_f32_e32 v84, 0xbfb8aa3b, v84
	v_exp_f32_e32 v84, v84
	v_mul_f32_e32 v85, 0xbfb8aa3b, v85
	v_exp_f32_e32 v85, v85
	v_mul_f32_e32 v86, 0xbfb8aa3b, v86
	v_exp_f32_e32 v86, v86
	v_mul_f32_e32 v87, 0xbfb8aa3b, v87
	v_exp_f32_e32 v87, v87
	v_add_f32_e32 v84, 1.0, v84
	v_rcp_f32_e32 v84, v84
	v_add_f32_e32 v85, 1.0, v85
	v_rcp_f32_e32 v85, v85
	v_add_f32_e32 v86, 1.0, v86
	v_rcp_f32_e32 v86, v86
	v_add_f32_e32 v87, 1.0, v87
	v_rcp_f32_e32 v87, v87
	v_sub_f32_e32 v92, 1.0, v88
	v_fma_f32 v84, v84, v92, v88
	v_sub_f32_e32 v88, 1.0, v89
	v_fma_f32 v85, v85, v88, v89
	v_sub_f32_e32 v88, 1.0, v90
	v_fma_f32 v86, v86, v88, v90
	v_sub_f32_e32 v88, 1.0, v91
	v_fmac_f32_e32 v91, v87, v88
	v_log_f32_e32 v84, v84
	v_log_f32_e32 v85, v85
	v_log_f32_e32 v86, v86
	v_log_f32_e32 v87, v91
	v_pk_mul_f32 v[84:85], v[84:85], s[96:97] op_sel_hi:[1,0]
	v_pk_mul_f32 v[86:87], v[86:87], s[96:97] op_sel_hi:[1,0]

.LBB0_208:
	v_cmp_ne_u32_e32 vcc, 3, v127
	s_and_saveexec_b64 s[8:9], vcc
	s_cbranch_execz .LBB0_210
	v_and_b32_e32 v88, 0xfffff800, v125
	v_add_u32_e32 v88, 0xfffff800, v88
	v_ashrrev_i32_e32 v89, 31, v88
	v_lshl_add_u64 v[88:89], v[88:89], 2, s[90:91]
	v_lshlrev_b32_e32 v90, 2, v124
	v_mov_b32_e32 v91, v177
	v_lshl_add_u64 v[88:89], v[88:89], 0, v[90:91]
	v_mov_b64_e32 v[88:89], v[156:157]
	v_mov_b64_e32 v[90:91], v[158:159]
	v_mul_f32_e32 v80, 0xbfb8aa3b, v80
	v_exp_f32_e32 v80, v80
	v_mul_f32_e32 v81, 0xbfb8aa3b, v81
	v_exp_f32_e32 v81, v81
	v_mul_f32_e32 v82, 0xbfb8aa3b, v82
	v_exp_f32_e32 v82, v82
	v_mul_f32_e32 v83, 0xbfb8aa3b, v83
	v_exp_f32_e32 v83, v83
	v_add_f32_e32 v80, 1.0, v80
	v_rcp_f32_e32 v80, v80
	v_add_f32_e32 v81, 1.0, v81
	v_rcp_f32_e32 v81, v81
	v_add_f32_e32 v82, 1.0, v82
	v_rcp_f32_e32 v82, v82
	v_add_f32_e32 v83, 1.0, v83
	v_rcp_f32_e32 v83, v83
	v_sub_f32_e32 v92, 1.0, v88
	v_fma_f32 v80, v80, v92, v88
	v_sub_f32_e32 v88, 1.0, v89
	v_fma_f32 v81, v81, v88, v89
	v_sub_f32_e32 v88, 1.0, v90
	v_fma_f32 v82, v82, v88, v90
	v_sub_f32_e32 v88, 1.0, v91
	v_fmac_f32_e32 v91, v83, v88
	v_log_f32_e32 v80, v80
	v_log_f32_e32 v81, v81
	v_log_f32_e32 v82, v82
	v_log_f32_e32 v83, v91
	v_pk_mul_f32 v[80:81], v[80:81], s[96:97] op_sel_hi:[1,0]
	v_pk_mul_f32 v[82:83], v[82:83], s[96:97] op_sel_hi:[1,0]

.LBB0_215:
	s_or_b64 exec, exec, s[2:3]
	v_cvt_pk_bf16_f32 v88, v80, v81
	v_lshl_add_u64 v[80:81], v[112:113], 0, v[96:97]
	v_lshlrev_b64 v[80:81], 12, v[80:81]
	v_cvt_pk_bf16_f32 v87, v86, v87
	v_cvt_pk_bf16_f32 v86, v84, v85
	v_cvt_pk_bf16_f32 v89, v82, v83
	v_lshl_add_u64 v[80:81], s[86:87], 0, v[80:81]
	v_mov_b32_e32 v115, v177
	v_permlane16_swap_b32_e32 v86, v88
	v_permlane16_swap_b32_e32 v87, v89
	v_lshl_add_u64 v[80:81], v[80:81], 0, v[114:115]
	global_store_dwordx4 v[80:81], v[86:89], off
	s_and_saveexec_b64 s[2:3], s[44:45]
	s_xor_b64 s[2:3], exec, s[2:3]
	s_cbranch_execz .LBB0_223
	v_cmp_ne_u32_e32 vcc, 3, v133
	s_and_saveexec_b64 s[8:9], vcc
	s_cbranch_execz .LBB0_218
	v_and_b32_e32 v80, 0xfffff800, v131
	v_add_u32_e32 v80, 0xfffff800, v80
	v_ashrrev_i32_e32 v81, 31, v80
	v_lshl_add_u64 v[80:81], v[80:81], 2, s[90:91]
	v_lshlrev_b32_e32 v82, 2, v130
	v_mov_b32_e32 v83, v177
	v_lshl_add_u64 v[80:81], v[80:81], 0, v[82:83]
	v_mov_b64_e32 v[80:81], v[144:145]
	v_mov_b64_e32 v[82:83], v[146:147]
	v_mul_f32_e32 v76, 0xbfb8aa3b, v76
	v_exp_f32_e32 v76, v76
	v_mul_f32_e32 v77, 0xbfb8aa3b, v77
	v_exp_f32_e32 v77, v77
	v_mul_f32_e32 v78, 0xbfb8aa3b, v78
	v_exp_f32_e32 v78, v78
	v_mul_f32_e32 v79, 0xbfb8aa3b, v79
	v_exp_f32_e32 v79, v79
	v_add_f32_e32 v76, 1.0, v76
	v_rcp_f32_e32 v76, v76
	v_add_f32_e32 v77, 1.0, v77
	v_rcp_f32_e32 v77, v77
	v_add_f32_e32 v78, 1.0, v78
	v_rcp_f32_e32 v78, v78
	v_add_f32_e32 v79, 1.0, v79
	v_rcp_f32_e32 v79, v79
	v_sub_f32_e32 v84, 1.0, v80
	v_fma_f32 v76, v76, v84, v80
	v_sub_f32_e32 v80, 1.0, v81
	v_fma_f32 v77, v77, v80, v81
	v_sub_f32_e32 v80, 1.0, v82
	v_fma_f32 v78, v78, v80, v82
	v_sub_f32_e32 v80, 1.0, v83
	v_fmac_f32_e32 v83, v79, v80
	v_log_f32_e32 v76, v76
	v_log_f32_e32 v77, v77
	v_log_f32_e32 v78, v78
	v_log_f32_e32 v79, v83
	v_pk_mul_f32 v[76:77], v[76:77], s[96:97] op_sel_hi:[1,0]
	v_pk_mul_f32 v[78:79], v[78:79], s[96:97] op_sel_hi:[1,0]

.LBB0_220:
	v_cmp_ne_u32_e32 vcc, 3, v135
	s_and_saveexec_b64 s[8:9], vcc
	s_cbranch_execz .LBB0_222
	v_and_b32_e32 v80, 0xfffff800, v134
	v_add_u32_e32 v80, 0xfffff800, v80
	v_ashrrev_i32_e32 v81, 31, v80
	v_lshl_add_u64 v[80:81], v[80:81], 2, s[90:91]
	v_lshlrev_b32_e32 v82, 2, v132
	v_mov_b32_e32 v83, v177
	v_lshl_add_u64 v[80:81], v[80:81], 0, v[82:83]
	v_mov_b64_e32 v[80:81], v[148:149]
	v_mov_b64_e32 v[82:83], v[150:151]
	v_mul_f32_e32 v72, 0xbfb8aa3b, v72
	v_exp_f32_e32 v72, v72
	v_mul_f32_e32 v73, 0xbfb8aa3b, v73
	v_exp_f32_e32 v73, v73
	v_mul_f32_e32 v74, 0xbfb8aa3b, v74
	v_exp_f32_e32 v74, v74
	v_mul_f32_e32 v75, 0xbfb8aa3b, v75
	v_exp_f32_e32 v75, v75
	v_add_f32_e32 v72, 1.0, v72
	v_rcp_f32_e32 v72, v72
	v_add_f32_e32 v73, 1.0, v73
	v_rcp_f32_e32 v73, v73
	v_add_f32_e32 v74, 1.0, v74
	v_rcp_f32_e32 v74, v74
	v_add_f32_e32 v75, 1.0, v75
	v_rcp_f32_e32 v75, v75
	v_sub_f32_e32 v84, 1.0, v80
	v_fma_f32 v72, v72, v84, v80
	v_sub_f32_e32 v80, 1.0, v81
	v_fma_f32 v73, v73, v80, v81
	v_sub_f32_e32 v80, 1.0, v82
	v_fma_f32 v74, v74, v80, v82
	v_sub_f32_e32 v80, 1.0, v83
	v_fmac_f32_e32 v83, v75, v80
	v_log_f32_e32 v72, v72
	v_log_f32_e32 v73, v73
	v_log_f32_e32 v74, v74
	v_log_f32_e32 v75, v83
	v_pk_mul_f32 v[72:73], v[72:73], s[96:97] op_sel_hi:[1,0]
	v_pk_mul_f32 v[74:75], v[74:75], s[96:97] op_sel_hi:[1,0]

.LBB0_227:
	s_or_b64 exec, exec, s[2:3]
	v_add_u32_e32 v80, 48, v128
	v_ashrrev_i32_e32 v81, 31, v80
	v_cvt_pk_bf16_f32 v84, v72, v73
	v_lshl_add_u64 v[72:73], v[120:121], 0, v[80:81]
	v_lshlrev_b64 v[72:73], 12, v[72:73]
	v_cvt_pk_bf16_f32 v83, v78, v79
	v_cvt_pk_bf16_f32 v82, v76, v77
	v_cvt_pk_bf16_f32 v85, v74, v75
	v_lshl_add_u64 v[72:73], s[86:87], 0, v[72:73]
	v_permlane16_swap_b32_e32 v82, v84
	v_permlane16_swap_b32_e32 v83, v85
	v_lshl_add_u64 v[72:73], v[72:73], 0, v[176:177]
	global_store_dwordx4 v[72:73], v[82:85], off
	s_and_saveexec_b64 s[2:3], s[48:49]
	s_xor_b64 s[2:3], exec, s[2:3]
	s_cbranch_execz .LBB0_235
	v_cmp_ne_u32_e32 vcc, 3, v126
	s_and_saveexec_b64 s[8:9], vcc
	s_cbranch_execz .LBB0_230
	v_and_b32_e32 v72, 0xfffff800, v123
	v_add_u32_e32 v72, 0xfffff800, v72
	v_ashrrev_i32_e32 v73, 31, v72
	v_lshl_add_u64 v[72:73], v[72:73], 2, s[90:91]
	v_lshlrev_b32_e32 v74, 2, v122
	v_mov_b32_e32 v75, v177
	v_lshl_add_u64 v[72:73], v[72:73], 0, v[74:75]
	v_mov_b64_e32 v[72:73], v[152:153]
	v_mov_b64_e32 v[74:75], v[154:155]
	v_mul_f32_e32 v68, 0xbfb8aa3b, v68
	v_exp_f32_e32 v68, v68
	v_mul_f32_e32 v69, 0xbfb8aa3b, v69
	v_exp_f32_e32 v69, v69
	v_mul_f32_e32 v70, 0xbfb8aa3b, v70
	v_exp_f32_e32 v70, v70
	v_mul_f32_e32 v71, 0xbfb8aa3b, v71
	v_exp_f32_e32 v71, v71
	v_add_f32_e32 v68, 1.0, v68
	v_rcp_f32_e32 v68, v68
	v_add_f32_e32 v69, 1.0, v69
	v_rcp_f32_e32 v69, v69
	v_add_f32_e32 v70, 1.0, v70
	v_rcp_f32_e32 v70, v70
	v_add_f32_e32 v71, 1.0, v71
	v_rcp_f32_e32 v71, v71
	v_sub_f32_e32 v76, 1.0, v72
	v_fma_f32 v68, v68, v76, v72
	v_sub_f32_e32 v72, 1.0, v73
	v_fma_f32 v69, v69, v72, v73
	v_sub_f32_e32 v72, 1.0, v74
	v_fma_f32 v70, v70, v72, v74
	v_sub_f32_e32 v72, 1.0, v75
	v_fmac_f32_e32 v75, v71, v72
	v_log_f32_e32 v68, v68
	v_log_f32_e32 v69, v69
	v_log_f32_e32 v70, v70
	v_log_f32_e32 v71, v75
	v_pk_mul_f32 v[68:69], v[68:69], s[96:97] op_sel_hi:[1,0]
	v_pk_mul_f32 v[70:71], v[70:71], s[96:97] op_sel_hi:[1,0]

.LBB0_232:
	v_cmp_ne_u32_e32 vcc, 3, v127
	s_and_saveexec_b64 s[8:9], vcc
	s_cbranch_execz .LBB0_234
	v_and_b32_e32 v72, 0xfffff800, v125
	v_add_u32_e32 v72, 0xfffff800, v72
	v_ashrrev_i32_e32 v73, 31, v72
	v_lshl_add_u64 v[72:73], v[72:73], 2, s[90:91]
	v_lshlrev_b32_e32 v74, 2, v124
	v_mov_b32_e32 v75, v177
	v_lshl_add_u64 v[72:73], v[72:73], 0, v[74:75]
	v_mov_b64_e32 v[72:73], v[156:157]
	v_mov_b64_e32 v[74:75], v[158:159]
	v_mul_f32_e32 v64, 0xbfb8aa3b, v64
	v_exp_f32_e32 v64, v64
	v_mul_f32_e32 v65, 0xbfb8aa3b, v65
	v_exp_f32_e32 v65, v65
	v_mul_f32_e32 v66, 0xbfb8aa3b, v66
	v_exp_f32_e32 v66, v66
	v_mul_f32_e32 v67, 0xbfb8aa3b, v67
	v_exp_f32_e32 v67, v67
	v_add_f32_e32 v64, 1.0, v64
	v_rcp_f32_e32 v64, v64
	v_add_f32_e32 v65, 1.0, v65
	v_rcp_f32_e32 v65, v65
	v_add_f32_e32 v66, 1.0, v66
	v_rcp_f32_e32 v66, v66
	v_add_f32_e32 v67, 1.0, v67
	v_rcp_f32_e32 v67, v67
	v_sub_f32_e32 v76, 1.0, v72
	v_fma_f32 v64, v64, v76, v72
	v_sub_f32_e32 v72, 1.0, v73
	v_fma_f32 v65, v65, v72, v73
	v_sub_f32_e32 v72, 1.0, v74
	v_fma_f32 v66, v66, v72, v74
	v_sub_f32_e32 v72, 1.0, v75
	v_fmac_f32_e32 v75, v67, v72
	v_log_f32_e32 v64, v64
	v_log_f32_e32 v65, v65
	v_log_f32_e32 v66, v66
	v_log_f32_e32 v67, v75
	v_pk_mul_f32 v[64:65], v[64:65], s[96:97] op_sel_hi:[1,0]
	v_pk_mul_f32 v[66:67], v[66:67], s[96:97] op_sel_hi:[1,0]

.LBB0_239:
	s_or_b64 exec, exec, s[2:3]
	v_cvt_pk_bf16_f32 v72, v64, v65
	v_lshl_add_u64 v[64:65], v[112:113], 0, v[80:81]
	v_lshlrev_b64 v[64:65], 12, v[64:65]
	v_cvt_pk_bf16_f32 v71, v70, v71
	v_cvt_pk_bf16_f32 v70, v68, v69
	v_cvt_pk_bf16_f32 v73, v66, v67
	v_lshl_add_u64 v[64:65], s[86:87], 0, v[64:65]
	v_mov_b32_e32 v115, v177
	v_permlane16_swap_b32_e32 v70, v72
	v_permlane16_swap_b32_e32 v71, v73
	v_lshl_add_u64 v[64:65], v[64:65], 0, v[114:115]
	global_store_dwordx4 v[64:65], v[70:73], off
	s_and_saveexec_b64 s[2:3], s[44:45]
	s_xor_b64 s[2:3], exec, s[2:3]
	s_cbranch_execz .LBB0_247
	v_cmp_ne_u32_e32 vcc, 3, v133
	s_and_saveexec_b64 s[8:9], vcc
	s_cbranch_execz .LBB0_242
	v_and_b32_e32 v64, 0xfffff800, v131
	v_add_u32_e32 v64, 0xfffff800, v64
	v_ashrrev_i32_e32 v65, 31, v64
	v_lshl_add_u64 v[64:65], v[64:65], 2, s[90:91]
	v_lshlrev_b32_e32 v66, 2, v130
	v_mov_b32_e32 v67, v177
	v_lshl_add_u64 v[64:65], v[64:65], 0, v[66:67]
	v_mov_b64_e32 v[64:65], v[144:145]
	v_mov_b64_e32 v[66:67], v[146:147]
	v_mul_f32_e32 v60, 0xbfb8aa3b, v60
	v_exp_f32_e32 v60, v60
	v_mul_f32_e32 v61, 0xbfb8aa3b, v61
	v_exp_f32_e32 v61, v61
	v_mul_f32_e32 v62, 0xbfb8aa3b, v62
	v_exp_f32_e32 v62, v62
	v_mul_f32_e32 v63, 0xbfb8aa3b, v63
	v_exp_f32_e32 v63, v63
	v_add_f32_e32 v60, 1.0, v60
	v_rcp_f32_e32 v60, v60
	v_add_f32_e32 v61, 1.0, v61
	v_rcp_f32_e32 v61, v61
	v_add_f32_e32 v62, 1.0, v62
	v_rcp_f32_e32 v62, v62
	v_add_f32_e32 v63, 1.0, v63
	v_rcp_f32_e32 v63, v63
	v_sub_f32_e32 v68, 1.0, v64
	v_fma_f32 v60, v60, v68, v64
	v_sub_f32_e32 v64, 1.0, v65
	v_fma_f32 v61, v61, v64, v65
	v_sub_f32_e32 v64, 1.0, v66
	v_fma_f32 v62, v62, v64, v66
	v_sub_f32_e32 v64, 1.0, v67
	v_fmac_f32_e32 v67, v63, v64
	v_log_f32_e32 v60, v60
	v_log_f32_e32 v61, v61
	v_log_f32_e32 v62, v62
	v_log_f32_e32 v63, v67
	v_pk_mul_f32 v[60:61], v[60:61], s[96:97] op_sel_hi:[1,0]
	v_pk_mul_f32 v[62:63], v[62:63], s[96:97] op_sel_hi:[1,0]

.LBB0_244:
	v_cmp_ne_u32_e32 vcc, 3, v135
	s_and_saveexec_b64 s[8:9], vcc
	s_cbranch_execz .LBB0_246
	v_and_b32_e32 v64, 0xfffff800, v134
	v_add_u32_e32 v64, 0xfffff800, v64
	v_ashrrev_i32_e32 v65, 31, v64
	v_lshl_add_u64 v[64:65], v[64:65], 2, s[90:91]
	v_lshlrev_b32_e32 v66, 2, v132
	v_mov_b32_e32 v67, v177
	v_lshl_add_u64 v[64:65], v[64:65], 0, v[66:67]
	v_mov_b64_e32 v[64:65], v[148:149]
	v_mov_b64_e32 v[66:67], v[150:151]
	v_mul_f32_e32 v56, 0xbfb8aa3b, v56
	v_exp_f32_e32 v56, v56
	v_mul_f32_e32 v57, 0xbfb8aa3b, v57
	v_exp_f32_e32 v57, v57
	v_mul_f32_e32 v58, 0xbfb8aa3b, v58
	v_exp_f32_e32 v58, v58
	v_mul_f32_e32 v59, 0xbfb8aa3b, v59
	v_exp_f32_e32 v59, v59
	v_add_f32_e32 v56, 1.0, v56
	v_rcp_f32_e32 v56, v56
	v_add_f32_e32 v57, 1.0, v57
	v_rcp_f32_e32 v57, v57
	v_add_f32_e32 v58, 1.0, v58
	v_rcp_f32_e32 v58, v58
	v_add_f32_e32 v59, 1.0, v59
	v_rcp_f32_e32 v59, v59
	v_sub_f32_e32 v68, 1.0, v64
	v_fma_f32 v56, v56, v68, v64
	v_sub_f32_e32 v64, 1.0, v65
	v_fma_f32 v57, v57, v64, v65
	v_sub_f32_e32 v64, 1.0, v66
	v_fma_f32 v58, v58, v64, v66
	v_sub_f32_e32 v64, 1.0, v67
	v_fmac_f32_e32 v67, v59, v64
	v_log_f32_e32 v56, v56
	v_log_f32_e32 v57, v57
	v_log_f32_e32 v58, v58
	v_log_f32_e32 v59, v67
	v_pk_mul_f32 v[56:57], v[56:57], s[96:97] op_sel_hi:[1,0]
	v_pk_mul_f32 v[58:59], v[58:59], s[96:97] op_sel_hi:[1,0]

.LBB0_251:
	s_or_b64 exec, exec, s[2:3]
	v_add_u32_e32 v64, 64, v128
	v_ashrrev_i32_e32 v65, 31, v64
	v_cvt_pk_bf16_f32 v68, v56, v57
	v_lshl_add_u64 v[56:57], v[120:121], 0, v[64:65]
	v_lshlrev_b64 v[56:57], 12, v[56:57]
	v_cvt_pk_bf16_f32 v67, v62, v63
	v_cvt_pk_bf16_f32 v66, v60, v61
	v_cvt_pk_bf16_f32 v69, v58, v59
	v_lshl_add_u64 v[56:57], s[86:87], 0, v[56:57]
	v_permlane16_swap_b32_e32 v66, v68
	v_permlane16_swap_b32_e32 v67, v69
	v_lshl_add_u64 v[56:57], v[56:57], 0, v[176:177]
	global_store_dwordx4 v[56:57], v[66:69], off
	s_and_saveexec_b64 s[2:3], s[48:49]
	s_xor_b64 s[2:3], exec, s[2:3]
	s_cbranch_execz .LBB0_259
	v_cmp_ne_u32_e32 vcc, 3, v126
	s_and_saveexec_b64 s[8:9], vcc
	s_cbranch_execz .LBB0_254
	v_and_b32_e32 v56, 0xfffff800, v123
	v_add_u32_e32 v56, 0xfffff800, v56
	v_ashrrev_i32_e32 v57, 31, v56
	v_lshl_add_u64 v[56:57], v[56:57], 2, s[90:91]
	v_lshlrev_b32_e32 v58, 2, v122
	v_mov_b32_e32 v59, v177
	v_lshl_add_u64 v[56:57], v[56:57], 0, v[58:59]
	v_mov_b64_e32 v[56:57], v[152:153]
	v_mov_b64_e32 v[58:59], v[154:155]
	v_mul_f32_e32 v52, 0xbfb8aa3b, v52
	v_exp_f32_e32 v52, v52
	v_mul_f32_e32 v53, 0xbfb8aa3b, v53
	v_exp_f32_e32 v53, v53
	v_mul_f32_e32 v54, 0xbfb8aa3b, v54
	v_exp_f32_e32 v54, v54
	v_mul_f32_e32 v55, 0xbfb8aa3b, v55
	v_exp_f32_e32 v55, v55
	v_add_f32_e32 v52, 1.0, v52
	v_rcp_f32_e32 v52, v52
	v_add_f32_e32 v53, 1.0, v53
	v_rcp_f32_e32 v53, v53
	v_add_f32_e32 v54, 1.0, v54
	v_rcp_f32_e32 v54, v54
	v_add_f32_e32 v55, 1.0, v55
	v_rcp_f32_e32 v55, v55
	v_sub_f32_e32 v60, 1.0, v56
	v_fma_f32 v52, v52, v60, v56
	v_sub_f32_e32 v56, 1.0, v57
	v_fma_f32 v53, v53, v56, v57
	v_sub_f32_e32 v56, 1.0, v58
	v_fma_f32 v54, v54, v56, v58
	v_sub_f32_e32 v56, 1.0, v59
	v_fmac_f32_e32 v59, v55, v56
	v_log_f32_e32 v52, v52
	v_log_f32_e32 v53, v53
	v_log_f32_e32 v54, v54
	v_log_f32_e32 v55, v59
	v_pk_mul_f32 v[52:53], v[52:53], s[96:97] op_sel_hi:[1,0]
	v_pk_mul_f32 v[54:55], v[54:55], s[96:97] op_sel_hi:[1,0]

.LBB0_256:
	v_cmp_ne_u32_e32 vcc, 3, v127
	s_and_saveexec_b64 s[8:9], vcc
	s_cbranch_execz .LBB0_258
	v_and_b32_e32 v56, 0xfffff800, v125
	v_add_u32_e32 v56, 0xfffff800, v56
	v_ashrrev_i32_e32 v57, 31, v56
	v_lshl_add_u64 v[56:57], v[56:57], 2, s[90:91]
	v_lshlrev_b32_e32 v58, 2, v124
	v_mov_b32_e32 v59, v177
	v_lshl_add_u64 v[56:57], v[56:57], 0, v[58:59]
	v_mov_b64_e32 v[56:57], v[156:157]
	v_mov_b64_e32 v[58:59], v[158:159]
	v_mul_f32_e32 v48, 0xbfb8aa3b, v48
	v_exp_f32_e32 v48, v48
	v_mul_f32_e32 v49, 0xbfb8aa3b, v49
	v_exp_f32_e32 v49, v49
	v_mul_f32_e32 v50, 0xbfb8aa3b, v50
	v_exp_f32_e32 v50, v50
	v_mul_f32_e32 v51, 0xbfb8aa3b, v51
	v_exp_f32_e32 v51, v51
	v_add_f32_e32 v48, 1.0, v48
	v_rcp_f32_e32 v48, v48
	v_add_f32_e32 v49, 1.0, v49
	v_rcp_f32_e32 v49, v49
	v_add_f32_e32 v50, 1.0, v50
	v_rcp_f32_e32 v50, v50
	v_add_f32_e32 v51, 1.0, v51
	v_rcp_f32_e32 v51, v51
	v_sub_f32_e32 v60, 1.0, v56
	v_fma_f32 v48, v48, v60, v56
	v_sub_f32_e32 v56, 1.0, v57
	v_fma_f32 v49, v49, v56, v57
	v_sub_f32_e32 v56, 1.0, v58
	v_fma_f32 v50, v50, v56, v58
	v_sub_f32_e32 v56, 1.0, v59
	v_fmac_f32_e32 v59, v51, v56
	v_log_f32_e32 v48, v48
	v_log_f32_e32 v49, v49
	v_log_f32_e32 v50, v50
	v_log_f32_e32 v51, v59
	v_pk_mul_f32 v[48:49], v[48:49], s[96:97] op_sel_hi:[1,0]
	v_pk_mul_f32 v[50:51], v[50:51], s[96:97] op_sel_hi:[1,0]

.LBB0_263:
	s_or_b64 exec, exec, s[2:3]
	v_cvt_pk_bf16_f32 v56, v48, v49
	v_lshl_add_u64 v[48:49], v[112:113], 0, v[64:65]
	v_lshlrev_b64 v[48:49], 12, v[48:49]
	v_cvt_pk_bf16_f32 v55, v54, v55
	v_cvt_pk_bf16_f32 v54, v52, v53
	v_cvt_pk_bf16_f32 v57, v50, v51
	v_lshl_add_u64 v[48:49], s[86:87], 0, v[48:49]
	v_mov_b32_e32 v115, v177
	v_permlane16_swap_b32_e32 v54, v56
	v_permlane16_swap_b32_e32 v55, v57
	v_lshl_add_u64 v[48:49], v[48:49], 0, v[114:115]
	global_store_dwordx4 v[48:49], v[54:57], off
	s_and_saveexec_b64 s[2:3], s[44:45]
	s_xor_b64 s[2:3], exec, s[2:3]
	s_cbranch_execz .LBB0_271
	v_cmp_ne_u32_e32 vcc, 3, v133
	s_and_saveexec_b64 s[8:9], vcc
	s_cbranch_execz .LBB0_266
	v_and_b32_e32 v48, 0xfffff800, v131
	v_add_u32_e32 v48, 0xfffff800, v48
	v_ashrrev_i32_e32 v49, 31, v48
	v_lshl_add_u64 v[48:49], v[48:49], 2, s[90:91]
	v_lshlrev_b32_e32 v50, 2, v130
	v_mov_b32_e32 v51, v177
	v_lshl_add_u64 v[48:49], v[48:49], 0, v[50:51]
	v_mov_b64_e32 v[48:49], v[144:145]
	v_mov_b64_e32 v[50:51], v[146:147]
	v_mul_f32_e32 v44, 0xbfb8aa3b, v44
	v_exp_f32_e32 v44, v44
	v_mul_f32_e32 v45, 0xbfb8aa3b, v45
	v_exp_f32_e32 v45, v45
	v_mul_f32_e32 v46, 0xbfb8aa3b, v46
	v_exp_f32_e32 v46, v46
	v_mul_f32_e32 v47, 0xbfb8aa3b, v47
	v_exp_f32_e32 v47, v47
	v_add_f32_e32 v44, 1.0, v44
	v_rcp_f32_e32 v44, v44
	v_add_f32_e32 v45, 1.0, v45
	v_rcp_f32_e32 v45, v45
	v_add_f32_e32 v46, 1.0, v46
	v_rcp_f32_e32 v46, v46
	v_add_f32_e32 v47, 1.0, v47
	v_rcp_f32_e32 v47, v47
	v_sub_f32_e32 v52, 1.0, v48
	v_fma_f32 v44, v44, v52, v48
	v_sub_f32_e32 v48, 1.0, v49
	v_fma_f32 v45, v45, v48, v49
	v_sub_f32_e32 v48, 1.0, v50
	v_fma_f32 v46, v46, v48, v50
	v_sub_f32_e32 v48, 1.0, v51
	v_fmac_f32_e32 v51, v47, v48
	v_log_f32_e32 v44, v44
	v_log_f32_e32 v45, v45
	v_log_f32_e32 v46, v46
	v_log_f32_e32 v47, v51
	v_pk_mul_f32 v[44:45], v[44:45], s[96:97] op_sel_hi:[1,0]
	v_pk_mul_f32 v[46:47], v[46:47], s[96:97] op_sel_hi:[1,0]

.LBB0_268:
	v_cmp_ne_u32_e32 vcc, 3, v135
	s_and_saveexec_b64 s[8:9], vcc
	s_cbranch_execz .LBB0_270
	v_and_b32_e32 v48, 0xfffff800, v134
	v_add_u32_e32 v48, 0xfffff800, v48
	v_ashrrev_i32_e32 v49, 31, v48
	v_lshl_add_u64 v[48:49], v[48:49], 2, s[90:91]
	v_lshlrev_b32_e32 v50, 2, v132
	v_mov_b32_e32 v51, v177
	v_lshl_add_u64 v[48:49], v[48:49], 0, v[50:51]
	v_mov_b64_e32 v[48:49], v[148:149]
	v_mov_b64_e32 v[50:51], v[150:151]
	v_mul_f32_e32 v40, 0xbfb8aa3b, v40
	v_exp_f32_e32 v40, v40
	v_mul_f32_e32 v41, 0xbfb8aa3b, v41
	v_exp_f32_e32 v41, v41
	v_mul_f32_e32 v42, 0xbfb8aa3b, v42
	v_exp_f32_e32 v42, v42
	v_mul_f32_e32 v43, 0xbfb8aa3b, v43
	v_exp_f32_e32 v43, v43
	v_add_f32_e32 v40, 1.0, v40
	v_rcp_f32_e32 v40, v40
	v_add_f32_e32 v41, 1.0, v41
	v_rcp_f32_e32 v41, v41
	v_add_f32_e32 v42, 1.0, v42
	v_rcp_f32_e32 v42, v42
	v_add_f32_e32 v43, 1.0, v43
	v_rcp_f32_e32 v43, v43
	v_sub_f32_e32 v52, 1.0, v48
	v_fma_f32 v40, v40, v52, v48
	v_sub_f32_e32 v48, 1.0, v49
	v_fma_f32 v41, v41, v48, v49
	v_sub_f32_e32 v48, 1.0, v50
	v_fma_f32 v42, v42, v48, v50
	v_sub_f32_e32 v48, 1.0, v51
	v_fmac_f32_e32 v51, v43, v48
	v_log_f32_e32 v40, v40
	v_log_f32_e32 v41, v41
	v_log_f32_e32 v42, v42
	v_log_f32_e32 v43, v51
	v_pk_mul_f32 v[40:41], v[40:41], s[96:97] op_sel_hi:[1,0]
	v_pk_mul_f32 v[42:43], v[42:43], s[96:97] op_sel_hi:[1,0]

.LBB0_275:
	s_or_b64 exec, exec, s[2:3]
	v_add_u32_e32 v48, 0x50, v128
	v_ashrrev_i32_e32 v49, 31, v48
	v_cvt_pk_bf16_f32 v52, v40, v41
	v_lshl_add_u64 v[40:41], v[120:121], 0, v[48:49]
	v_lshlrev_b64 v[40:41], 12, v[40:41]
	v_cvt_pk_bf16_f32 v51, v46, v47
	v_cvt_pk_bf16_f32 v50, v44, v45
	v_cvt_pk_bf16_f32 v53, v42, v43
	v_lshl_add_u64 v[40:41], s[86:87], 0, v[40:41]
	v_permlane16_swap_b32_e32 v50, v52
	v_permlane16_swap_b32_e32 v51, v53
	v_lshl_add_u64 v[40:41], v[40:41], 0, v[176:177]
	global_store_dwordx4 v[40:41], v[50:53], off
	s_and_saveexec_b64 s[2:3], s[48:49]
	s_xor_b64 s[2:3], exec, s[2:3]
	s_cbranch_execz .LBB0_283
	v_cmp_ne_u32_e32 vcc, 3, v126
	s_and_saveexec_b64 s[8:9], vcc
	s_cbranch_execz .LBB0_278
	v_and_b32_e32 v40, 0xfffff800, v123
	v_add_u32_e32 v40, 0xfffff800, v40
	v_ashrrev_i32_e32 v41, 31, v40
	v_lshl_add_u64 v[40:41], v[40:41], 2, s[90:91]
	v_lshlrev_b32_e32 v42, 2, v122
	v_mov_b32_e32 v43, v177
	v_lshl_add_u64 v[40:41], v[40:41], 0, v[42:43]
	v_mov_b64_e32 v[40:41], v[152:153]
	v_mov_b64_e32 v[42:43], v[154:155]
	v_mul_f32_e32 v36, 0xbfb8aa3b, v36
	v_exp_f32_e32 v36, v36
	v_mul_f32_e32 v37, 0xbfb8aa3b, v37
	v_exp_f32_e32 v37, v37
	v_mul_f32_e32 v38, 0xbfb8aa3b, v38
	v_exp_f32_e32 v38, v38
	v_mul_f32_e32 v39, 0xbfb8aa3b, v39
	v_exp_f32_e32 v39, v39
	v_add_f32_e32 v36, 1.0, v36
	v_rcp_f32_e32 v36, v36
	v_add_f32_e32 v37, 1.0, v37
	v_rcp_f32_e32 v37, v37
	v_add_f32_e32 v38, 1.0, v38
	v_rcp_f32_e32 v38, v38
	v_add_f32_e32 v39, 1.0, v39
	v_rcp_f32_e32 v39, v39
	v_sub_f32_e32 v44, 1.0, v40
	v_fma_f32 v36, v36, v44, v40
	v_sub_f32_e32 v40, 1.0, v41
	v_fma_f32 v37, v37, v40, v41
	v_sub_f32_e32 v40, 1.0, v42
	v_fma_f32 v38, v38, v40, v42
	v_sub_f32_e32 v40, 1.0, v43
	v_fmac_f32_e32 v43, v39, v40
	v_log_f32_e32 v36, v36
	v_log_f32_e32 v37, v37
	v_log_f32_e32 v38, v38
	v_log_f32_e32 v39, v43
	v_pk_mul_f32 v[36:37], v[36:37], s[96:97] op_sel_hi:[1,0]
	v_pk_mul_f32 v[38:39], v[38:39], s[96:97] op_sel_hi:[1,0]

.LBB0_280:
	v_cmp_ne_u32_e32 vcc, 3, v127
	s_and_saveexec_b64 s[8:9], vcc
	s_cbranch_execz .LBB0_282
	v_and_b32_e32 v40, 0xfffff800, v125
	v_add_u32_e32 v40, 0xfffff800, v40
	v_ashrrev_i32_e32 v41, 31, v40
	v_lshl_add_u64 v[40:41], v[40:41], 2, s[90:91]
	v_lshlrev_b32_e32 v42, 2, v124
	v_mov_b32_e32 v43, v177
	v_lshl_add_u64 v[40:41], v[40:41], 0, v[42:43]
	v_mov_b64_e32 v[40:41], v[156:157]
	v_mov_b64_e32 v[42:43], v[158:159]
	v_mul_f32_e32 v32, 0xbfb8aa3b, v32
	v_exp_f32_e32 v32, v32
	v_mul_f32_e32 v33, 0xbfb8aa3b, v33
	v_exp_f32_e32 v33, v33
	v_mul_f32_e32 v34, 0xbfb8aa3b, v34
	v_exp_f32_e32 v34, v34
	v_mul_f32_e32 v35, 0xbfb8aa3b, v35
	v_exp_f32_e32 v35, v35
	v_add_f32_e32 v32, 1.0, v32
	v_rcp_f32_e32 v32, v32
	v_add_f32_e32 v33, 1.0, v33
	v_rcp_f32_e32 v33, v33
	v_add_f32_e32 v34, 1.0, v34
	v_rcp_f32_e32 v34, v34
	v_add_f32_e32 v35, 1.0, v35
	v_rcp_f32_e32 v35, v35
	v_sub_f32_e32 v44, 1.0, v40
	v_fma_f32 v32, v32, v44, v40
	v_sub_f32_e32 v40, 1.0, v41
	v_fma_f32 v33, v33, v40, v41
	v_sub_f32_e32 v40, 1.0, v42
	v_fma_f32 v34, v34, v40, v42
	v_sub_f32_e32 v40, 1.0, v43
	v_fmac_f32_e32 v43, v35, v40
	v_log_f32_e32 v32, v32
	v_log_f32_e32 v33, v33
	v_log_f32_e32 v34, v34
	v_log_f32_e32 v35, v43
	v_pk_mul_f32 v[32:33], v[32:33], s[96:97] op_sel_hi:[1,0]
	v_pk_mul_f32 v[34:35], v[34:35], s[96:97] op_sel_hi:[1,0]

.LBB0_287:
	s_or_b64 exec, exec, s[2:3]
	v_cvt_pk_bf16_f32 v40, v32, v33
	v_lshl_add_u64 v[32:33], v[112:113], 0, v[48:49]
	v_lshlrev_b64 v[32:33], 12, v[32:33]
	v_cvt_pk_bf16_f32 v39, v38, v39
	v_cvt_pk_bf16_f32 v38, v36, v37
	v_cvt_pk_bf16_f32 v41, v34, v35
	v_lshl_add_u64 v[32:33], s[86:87], 0, v[32:33]
	v_mov_b32_e32 v115, v177
	v_permlane16_swap_b32_e32 v38, v40
	v_permlane16_swap_b32_e32 v39, v41
	v_lshl_add_u64 v[32:33], v[32:33], 0, v[114:115]
	global_store_dwordx4 v[32:33], v[38:41], off
	s_and_saveexec_b64 s[2:3], s[44:45]
	s_xor_b64 s[2:3], exec, s[2:3]
	s_cbranch_execz .LBB0_295
	v_cmp_ne_u32_e32 vcc, 3, v133
	s_and_saveexec_b64 s[8:9], vcc
	s_cbranch_execz .LBB0_290
	v_and_b32_e32 v32, 0xfffff800, v131
	v_add_u32_e32 v32, 0xfffff800, v32
	v_ashrrev_i32_e32 v33, 31, v32
	v_lshl_add_u64 v[32:33], v[32:33], 2, s[90:91]
	v_lshlrev_b32_e32 v34, 2, v130
	v_mov_b32_e32 v35, v177
	v_lshl_add_u64 v[32:33], v[32:33], 0, v[34:35]
	v_mov_b64_e32 v[32:33], v[144:145]
	v_mov_b64_e32 v[34:35], v[146:147]
	v_mul_f32_e32 v28, 0xbfb8aa3b, v28
	v_exp_f32_e32 v28, v28
	v_mul_f32_e32 v29, 0xbfb8aa3b, v29
	v_exp_f32_e32 v29, v29
	v_mul_f32_e32 v30, 0xbfb8aa3b, v30
	v_exp_f32_e32 v30, v30
	v_mul_f32_e32 v31, 0xbfb8aa3b, v31
	v_exp_f32_e32 v31, v31
	v_add_f32_e32 v28, 1.0, v28
	v_rcp_f32_e32 v28, v28
	v_add_f32_e32 v29, 1.0, v29
	v_rcp_f32_e32 v29, v29
	v_add_f32_e32 v30, 1.0, v30
	v_rcp_f32_e32 v30, v30
	v_add_f32_e32 v31, 1.0, v31
	v_rcp_f32_e32 v31, v31
	v_sub_f32_e32 v36, 1.0, v32
	v_fma_f32 v28, v28, v36, v32
	v_sub_f32_e32 v32, 1.0, v33
	v_fma_f32 v29, v29, v32, v33
	v_sub_f32_e32 v32, 1.0, v34
	v_fma_f32 v30, v30, v32, v34
	v_sub_f32_e32 v32, 1.0, v35
	v_fmac_f32_e32 v35, v31, v32
	v_log_f32_e32 v28, v28
	v_log_f32_e32 v29, v29
	v_log_f32_e32 v30, v30
	v_log_f32_e32 v31, v35
	v_pk_mul_f32 v[28:29], v[28:29], s[96:97] op_sel_hi:[1,0]
	v_pk_mul_f32 v[30:31], v[30:31], s[96:97] op_sel_hi:[1,0]

.LBB0_292:
	v_cmp_ne_u32_e32 vcc, 3, v135
	s_and_saveexec_b64 s[8:9], vcc
	s_cbranch_execz .LBB0_294
	v_and_b32_e32 v32, 0xfffff800, v134
	v_add_u32_e32 v32, 0xfffff800, v32
	v_ashrrev_i32_e32 v33, 31, v32
	v_lshl_add_u64 v[32:33], v[32:33], 2, s[90:91]
	v_lshlrev_b32_e32 v34, 2, v132
	v_mov_b32_e32 v35, v177
	v_lshl_add_u64 v[32:33], v[32:33], 0, v[34:35]
	v_mov_b64_e32 v[32:33], v[148:149]
	v_mov_b64_e32 v[34:35], v[150:151]
	v_mul_f32_e32 v24, 0xbfb8aa3b, v24
	v_exp_f32_e32 v24, v24
	v_mul_f32_e32 v25, 0xbfb8aa3b, v25
	v_exp_f32_e32 v25, v25
	v_mul_f32_e32 v26, 0xbfb8aa3b, v26
	v_exp_f32_e32 v26, v26
	v_mul_f32_e32 v27, 0xbfb8aa3b, v27
	v_exp_f32_e32 v27, v27
	v_add_f32_e32 v24, 1.0, v24
	v_rcp_f32_e32 v24, v24
	v_add_f32_e32 v25, 1.0, v25
	v_rcp_f32_e32 v25, v25
	v_add_f32_e32 v26, 1.0, v26
	v_rcp_f32_e32 v26, v26
	v_add_f32_e32 v27, 1.0, v27
	v_rcp_f32_e32 v27, v27
	v_sub_f32_e32 v36, 1.0, v32
	v_fma_f32 v24, v24, v36, v32
	v_sub_f32_e32 v32, 1.0, v33
	v_fma_f32 v25, v25, v32, v33
	v_sub_f32_e32 v32, 1.0, v34
	v_fma_f32 v26, v26, v32, v34
	v_sub_f32_e32 v32, 1.0, v35
	v_fmac_f32_e32 v35, v27, v32
	v_log_f32_e32 v24, v24
	v_log_f32_e32 v25, v25
	v_log_f32_e32 v26, v26
	v_log_f32_e32 v27, v35
	v_pk_mul_f32 v[24:25], v[24:25], s[96:97] op_sel_hi:[1,0]
	v_pk_mul_f32 v[26:27], v[26:27], s[96:97] op_sel_hi:[1,0]

.LBB0_299:
	s_or_b64 exec, exec, s[2:3]
	v_add_u32_e32 v32, 0x60, v128
	v_ashrrev_i32_e32 v33, 31, v32
	v_cvt_pk_bf16_f32 v36, v24, v25
	v_lshl_add_u64 v[24:25], v[120:121], 0, v[32:33]
	v_lshlrev_b64 v[24:25], 12, v[24:25]
	v_cvt_pk_bf16_f32 v35, v30, v31
	v_cvt_pk_bf16_f32 v34, v28, v29
	v_cvt_pk_bf16_f32 v37, v26, v27
	v_lshl_add_u64 v[24:25], s[86:87], 0, v[24:25]
	v_permlane16_swap_b32_e32 v34, v36
	v_permlane16_swap_b32_e32 v35, v37
	v_lshl_add_u64 v[24:25], v[24:25], 0, v[176:177]
	global_store_dwordx4 v[24:25], v[34:37], off
	s_and_saveexec_b64 s[2:3], s[48:49]
	s_xor_b64 s[2:3], exec, s[2:3]
	s_cbranch_execz .LBB0_307
	v_cmp_ne_u32_e32 vcc, 3, v126
	s_and_saveexec_b64 s[8:9], vcc
	s_cbranch_execz .LBB0_302
	v_and_b32_e32 v24, 0xfffff800, v123
	v_add_u32_e32 v24, 0xfffff800, v24
	v_ashrrev_i32_e32 v25, 31, v24
	v_lshl_add_u64 v[24:25], v[24:25], 2, s[90:91]
	v_lshlrev_b32_e32 v26, 2, v122
	v_mov_b32_e32 v27, v177
	v_lshl_add_u64 v[24:25], v[24:25], 0, v[26:27]
	v_mov_b64_e32 v[24:25], v[152:153]
	v_mov_b64_e32 v[26:27], v[154:155]
	v_mul_f32_e32 v20, 0xbfb8aa3b, v20
	v_exp_f32_e32 v20, v20
	v_mul_f32_e32 v21, 0xbfb8aa3b, v21
	v_exp_f32_e32 v21, v21
	v_mul_f32_e32 v22, 0xbfb8aa3b, v22
	v_exp_f32_e32 v22, v22
	v_mul_f32_e32 v23, 0xbfb8aa3b, v23
	v_exp_f32_e32 v23, v23
	v_add_f32_e32 v20, 1.0, v20
	v_rcp_f32_e32 v20, v20
	v_add_f32_e32 v21, 1.0, v21
	v_rcp_f32_e32 v21, v21
	v_add_f32_e32 v22, 1.0, v22
	v_rcp_f32_e32 v22, v22
	v_add_f32_e32 v23, 1.0, v23
	v_rcp_f32_e32 v23, v23
	v_sub_f32_e32 v28, 1.0, v24
	v_fma_f32 v20, v20, v28, v24
	v_sub_f32_e32 v24, 1.0, v25
	v_fma_f32 v21, v21, v24, v25
	v_sub_f32_e32 v24, 1.0, v26
	v_fma_f32 v22, v22, v24, v26
	v_sub_f32_e32 v24, 1.0, v27
	v_fmac_f32_e32 v27, v23, v24
	v_log_f32_e32 v20, v20
	v_log_f32_e32 v21, v21
	v_log_f32_e32 v22, v22
	v_log_f32_e32 v23, v27
	v_pk_mul_f32 v[20:21], v[20:21], s[96:97] op_sel_hi:[1,0]
	v_pk_mul_f32 v[22:23], v[22:23], s[96:97] op_sel_hi:[1,0]

.LBB0_304:
	v_cmp_ne_u32_e32 vcc, 3, v127
	s_and_saveexec_b64 s[8:9], vcc
	s_cbranch_execz .LBB0_306
	v_and_b32_e32 v24, 0xfffff800, v125
	v_add_u32_e32 v24, 0xfffff800, v24
	v_ashrrev_i32_e32 v25, 31, v24
	v_lshl_add_u64 v[24:25], v[24:25], 2, s[90:91]
	v_lshlrev_b32_e32 v26, 2, v124
	v_mov_b32_e32 v27, v177
	v_lshl_add_u64 v[24:25], v[24:25], 0, v[26:27]
	v_mov_b64_e32 v[24:25], v[156:157]
	v_mov_b64_e32 v[26:27], v[158:159]
	v_mul_f32_e32 v16, 0xbfb8aa3b, v16
	v_exp_f32_e32 v16, v16
	v_mul_f32_e32 v17, 0xbfb8aa3b, v17
	v_exp_f32_e32 v17, v17
	v_mul_f32_e32 v18, 0xbfb8aa3b, v18
	v_exp_f32_e32 v18, v18
	v_mul_f32_e32 v19, 0xbfb8aa3b, v19
	v_exp_f32_e32 v19, v19
	v_add_f32_e32 v16, 1.0, v16
	v_rcp_f32_e32 v16, v16
	v_add_f32_e32 v17, 1.0, v17
	v_rcp_f32_e32 v17, v17
	v_add_f32_e32 v18, 1.0, v18
	v_rcp_f32_e32 v18, v18
	v_add_f32_e32 v19, 1.0, v19
	v_rcp_f32_e32 v19, v19
	v_sub_f32_e32 v28, 1.0, v24
	v_fma_f32 v16, v16, v28, v24
	v_sub_f32_e32 v24, 1.0, v25
	v_fma_f32 v17, v17, v24, v25
	v_sub_f32_e32 v24, 1.0, v26
	v_fma_f32 v18, v18, v24, v26
	v_sub_f32_e32 v24, 1.0, v27
	v_fmac_f32_e32 v27, v19, v24
	v_log_f32_e32 v16, v16
	v_log_f32_e32 v17, v17
	v_log_f32_e32 v18, v18
	v_log_f32_e32 v19, v27
	v_pk_mul_f32 v[16:17], v[16:17], s[96:97] op_sel_hi:[1,0]
	v_pk_mul_f32 v[18:19], v[18:19], s[96:97] op_sel_hi:[1,0]

.LBB0_311:
	s_or_b64 exec, exec, s[2:3]
	v_cvt_pk_bf16_f32 v24, v16, v17
	v_lshl_add_u64 v[16:17], v[112:113], 0, v[32:33]
	v_lshlrev_b64 v[16:17], 12, v[16:17]
	v_cvt_pk_bf16_f32 v23, v22, v23
	v_cvt_pk_bf16_f32 v22, v20, v21
	v_cvt_pk_bf16_f32 v25, v18, v19
	v_lshl_add_u64 v[16:17], s[86:87], 0, v[16:17]
	v_mov_b32_e32 v115, v177
	v_permlane16_swap_b32_e32 v22, v24
	v_permlane16_swap_b32_e32 v23, v25
	v_lshl_add_u64 v[16:17], v[16:17], 0, v[114:115]
	global_store_dwordx4 v[16:17], v[22:25], off
	s_and_saveexec_b64 s[2:3], s[44:45]
	s_xor_b64 s[2:3], exec, s[2:3]
	s_cbranch_execz .LBB0_319
	v_cmp_ne_u32_e32 vcc, 3, v133
	s_and_saveexec_b64 s[8:9], vcc
	s_cbranch_execz .LBB0_314
	v_and_b32_e32 v16, 0xfffff800, v131
	v_add_u32_e32 v16, 0xfffff800, v16
	v_ashrrev_i32_e32 v17, 31, v16
	v_lshl_add_u64 v[16:17], v[16:17], 2, s[90:91]
	v_lshlrev_b32_e32 v18, 2, v130
	v_mov_b32_e32 v19, v177
	v_lshl_add_u64 v[16:17], v[16:17], 0, v[18:19]
	v_mov_b64_e32 v[16:17], v[144:145]
	v_mov_b64_e32 v[18:19], v[146:147]
	v_mul_f32_e32 v12, 0xbfb8aa3b, v12
	v_exp_f32_e32 v12, v12
	v_mul_f32_e32 v13, 0xbfb8aa3b, v13
	v_exp_f32_e32 v13, v13
	v_mul_f32_e32 v14, 0xbfb8aa3b, v14
	v_exp_f32_e32 v14, v14
	v_mul_f32_e32 v15, 0xbfb8aa3b, v15
	v_exp_f32_e32 v15, v15
	v_add_f32_e32 v12, 1.0, v12
	v_rcp_f32_e32 v12, v12
	v_add_f32_e32 v13, 1.0, v13
	v_rcp_f32_e32 v13, v13
	v_add_f32_e32 v14, 1.0, v14
	v_rcp_f32_e32 v14, v14
	v_add_f32_e32 v15, 1.0, v15
	v_rcp_f32_e32 v15, v15
	v_sub_f32_e32 v20, 1.0, v16
	v_fma_f32 v12, v12, v20, v16
	v_sub_f32_e32 v16, 1.0, v17
	v_fma_f32 v13, v13, v16, v17
	v_sub_f32_e32 v16, 1.0, v18
	v_fma_f32 v14, v14, v16, v18
	v_sub_f32_e32 v16, 1.0, v19
	v_fmac_f32_e32 v19, v15, v16
	v_log_f32_e32 v12, v12
	v_log_f32_e32 v13, v13
	v_log_f32_e32 v14, v14
	v_log_f32_e32 v15, v19
	v_pk_mul_f32 v[12:13], v[12:13], s[96:97] op_sel_hi:[1,0]
	v_pk_mul_f32 v[14:15], v[14:15], s[96:97] op_sel_hi:[1,0]

.LBB0_316:
	v_cmp_ne_u32_e32 vcc, 3, v135
	s_and_saveexec_b64 s[8:9], vcc
	s_cbranch_execz .LBB0_318
	v_and_b32_e32 v16, 0xfffff800, v134
	v_add_u32_e32 v16, 0xfffff800, v16
	v_ashrrev_i32_e32 v17, 31, v16
	v_lshl_add_u64 v[16:17], v[16:17], 2, s[90:91]
	v_lshlrev_b32_e32 v18, 2, v132
	v_mov_b32_e32 v19, v177
	v_lshl_add_u64 v[16:17], v[16:17], 0, v[18:19]
	v_mov_b64_e32 v[16:17], v[148:149]
	v_mov_b64_e32 v[18:19], v[150:151]
	v_mul_f32_e32 v8, 0xbfb8aa3b, v8
	v_exp_f32_e32 v8, v8
	v_mul_f32_e32 v9, 0xbfb8aa3b, v9
	v_exp_f32_e32 v9, v9
	v_mul_f32_e32 v10, 0xbfb8aa3b, v10
	v_exp_f32_e32 v10, v10
	v_mul_f32_e32 v11, 0xbfb8aa3b, v11
	v_exp_f32_e32 v11, v11
	v_add_f32_e32 v8, 1.0, v8
	v_rcp_f32_e32 v8, v8
	v_add_f32_e32 v9, 1.0, v9
	v_rcp_f32_e32 v9, v9
	v_add_f32_e32 v10, 1.0, v10
	v_rcp_f32_e32 v10, v10
	v_add_f32_e32 v11, 1.0, v11
	v_rcp_f32_e32 v11, v11
	v_sub_f32_e32 v20, 1.0, v16
	v_fma_f32 v8, v8, v20, v16
	v_sub_f32_e32 v16, 1.0, v17
	v_fma_f32 v9, v9, v16, v17
	v_sub_f32_e32 v16, 1.0, v18
	v_fma_f32 v10, v10, v16, v18
	v_sub_f32_e32 v16, 1.0, v19
	v_fmac_f32_e32 v19, v11, v16
	v_log_f32_e32 v8, v8
	v_log_f32_e32 v9, v9
	v_log_f32_e32 v10, v10
	v_log_f32_e32 v11, v19
	v_pk_mul_f32 v[8:9], v[8:9], s[96:97] op_sel_hi:[1,0]
	v_pk_mul_f32 v[10:11], v[10:11], s[96:97] op_sel_hi:[1,0]

.LBB0_323:
	s_or_b64 exec, exec, s[2:3]
	v_add_u32_e32 v16, 0x70, v128
	v_ashrrev_i32_e32 v17, 31, v16
	v_cvt_pk_bf16_f32 v20, v8, v9
	v_lshl_add_u64 v[8:9], v[120:121], 0, v[16:17]
	v_lshlrev_b64 v[8:9], 12, v[8:9]
	v_cvt_pk_bf16_f32 v19, v14, v15
	v_cvt_pk_bf16_f32 v18, v12, v13
	v_cvt_pk_bf16_f32 v21, v10, v11
	v_lshl_add_u64 v[8:9], s[86:87], 0, v[8:9]
	v_permlane16_swap_b32_e32 v18, v20
	v_permlane16_swap_b32_e32 v19, v21
	v_lshl_add_u64 v[8:9], v[8:9], 0, v[176:177]
	global_store_dwordx4 v[8:9], v[18:21], off
	s_and_saveexec_b64 s[2:3], s[48:49]
	s_xor_b64 s[2:3], exec, s[2:3]
	s_cbranch_execz .LBB0_331
	v_cmp_ne_u32_e32 vcc, 3, v126
	s_and_saveexec_b64 s[8:9], vcc
	s_cbranch_execz .LBB0_326
	v_and_b32_e32 v8, 0xfffff800, v123
	v_add_u32_e32 v8, 0xfffff800, v8
	v_ashrrev_i32_e32 v9, 31, v8
	v_lshl_add_u64 v[8:9], v[8:9], 2, s[90:91]
	v_lshlrev_b32_e32 v176, 2, v122
	v_lshl_add_u64 v[8:9], v[8:9], 0, v[176:177]
	v_mov_b64_e32 v[8:9], v[152:153]
	v_mov_b64_e32 v[10:11], v[154:155]
	v_mul_f32_e32 v4, 0xbfb8aa3b, v4
	v_exp_f32_e32 v4, v4
	v_mul_f32_e32 v5, 0xbfb8aa3b, v5
	v_exp_f32_e32 v5, v5
	v_mul_f32_e32 v6, 0xbfb8aa3b, v6
	v_exp_f32_e32 v6, v6
	v_mul_f32_e32 v7, 0xbfb8aa3b, v7
	v_exp_f32_e32 v7, v7
	v_add_f32_e32 v4, 1.0, v4
	v_rcp_f32_e32 v4, v4
	v_add_f32_e32 v5, 1.0, v5
	v_rcp_f32_e32 v5, v5
	v_add_f32_e32 v6, 1.0, v6
	v_rcp_f32_e32 v6, v6
	v_add_f32_e32 v7, 1.0, v7
	v_rcp_f32_e32 v7, v7
	v_sub_f32_e32 v12, 1.0, v8
	v_fma_f32 v4, v4, v12, v8
	v_sub_f32_e32 v8, 1.0, v9
	v_fma_f32 v5, v5, v8, v9
	v_sub_f32_e32 v8, 1.0, v10
	v_fma_f32 v6, v6, v8, v10
	v_sub_f32_e32 v8, 1.0, v11
	v_fmac_f32_e32 v11, v7, v8
	v_log_f32_e32 v4, v4
	v_log_f32_e32 v5, v5
	v_log_f32_e32 v6, v6
	v_log_f32_e32 v7, v11
	v_pk_mul_f32 v[4:5], v[4:5], s[96:97] op_sel_hi:[1,0]
	v_pk_mul_f32 v[6:7], v[6:7], s[96:97] op_sel_hi:[1,0]

.LBB0_328:
	v_cmp_ne_u32_e32 vcc, 3, v127
	s_and_saveexec_b64 s[2:3], vcc
	s_cbranch_execz .LBB0_330
	v_and_b32_e32 v8, 0xfffff800, v125
	v_add_u32_e32 v8, 0xfffff800, v8
	v_ashrrev_i32_e32 v9, 31, v8
	v_lshl_add_u64 v[8:9], v[8:9], 2, s[90:91]
	v_lshlrev_b32_e32 v176, 2, v124
	v_lshl_add_u64 v[8:9], v[8:9], 0, v[176:177]
	v_mov_b64_e32 v[8:9], v[156:157]
	v_mov_b64_e32 v[10:11], v[158:159]
	v_mul_f32_e32 v0, 0xbfb8aa3b, v0
	v_exp_f32_e32 v0, v0
	v_mul_f32_e32 v1, 0xbfb8aa3b, v1
	v_exp_f32_e32 v1, v1
	v_mul_f32_e32 v2, 0xbfb8aa3b, v2
	v_exp_f32_e32 v2, v2
	v_mul_f32_e32 v3, 0xbfb8aa3b, v3
	v_exp_f32_e32 v3, v3
	v_add_f32_e32 v0, 1.0, v0
	v_rcp_f32_e32 v0, v0
	v_add_f32_e32 v1, 1.0, v1
	v_rcp_f32_e32 v1, v1
	v_add_f32_e32 v2, 1.0, v2
	v_rcp_f32_e32 v2, v2
	v_add_f32_e32 v3, 1.0, v3
	v_rcp_f32_e32 v3, v3
	v_sub_f32_e32 v12, 1.0, v8
	v_fma_f32 v0, v0, v12, v8
	v_sub_f32_e32 v8, 1.0, v9
	v_fma_f32 v1, v1, v8, v9
	v_sub_f32_e32 v8, 1.0, v10
	v_fma_f32 v2, v2, v8, v10
	v_sub_f32_e32 v8, 1.0, v11
	v_fmac_f32_e32 v11, v3, v8
	v_log_f32_e32 v0, v0
	v_log_f32_e32 v1, v1
	v_log_f32_e32 v2, v2
	v_log_f32_e32 v3, v11
	v_pk_mul_f32 v[0:1], v[0:1], s[96:97] op_sel_hi:[1,0]
	v_pk_mul_f32 v[2:3], v[2:3], s[96:97] op_sel_hi:[1,0]
